# GEMM K-loop: LDS-DMA pieces in SGPR-base + 32-bit VGPR offset form (no per-piece 64-bit VALU adds), issued before the fragment ds_reads
# baseline (speedup 1.0000x reference)
; #define PG8_STAGE(bufoff, gbase, voff) do { _Pragma("unroll") for (int _i = 0; _i < 2; ++_i) \
;         __builtin_amdgcn_global_load_lds((const unsigned*)((const char*)(gbase) + (voff)[_i]), (LAS unsigned*)(lds + (bufoff) + ldsw + _i * 8192), 16, 0, 0); } while (0)
; #define PG8_LDA(dst, b, h) do { _Pragma("unroll") for (int m = 0; m < 4; ++m) _Pragma("unroll") for (int k = 0; k < 2; ++k) dst[m][k] = *(const LAS bf16x8*)(lds + PG8_SA(b, h) + aoff + m * 2048 + k * 1024); } while (0)
; #define PG8_LDB(dst, b, h) do { _Pragma("unroll") for (int n = 0; n < 2; ++n) _Pragma("unroll") for (int k = 0; k < 2; ++k) dst[n][k] = *(const LAS bf16x8*)(lds + PG8_SB(b, h) + boff + n * 2048 + k * 1024); } while (0)
; #define PG8_WAIT_V(n) asm volatile("s_waitcnt vmcnt(" #n ")" ::: "memory")
; #define PG8_BAR __builtin_amdgcn_s_barrier()
; template <class Epi>
; __device__ __forceinline__ void gemm_phase(LAS unsigned char* lds, const Gemm g, const StaticOrder& S, const Epi& E, const int tid) {
;     ...
;         for (int t = 0; t < nt; t += 2) {
;             const bool last = (t == nt - 2);
;             const char* a1 = cA + (size_t)(t + 1) * kstep;
;             const char* a2 = last ? nA : cA + (size_t)(t + 2) * kstep; const char* b2 = last ? nB : cB + (size_t)(t + 2) * kstep;
;             const char* a3 = a2 + kstep; const char* b3 = b2 + kstep;
;             PG8_LDB(B0, 0, 0); PG8_LDB(B1, 0, 1); PG8_SCHED; PG8_LDA(At, 0, 0); PG8_STAGE(PG8_SA(1, 1), a1 + hstepA, voffA);
;             PG8_WAIT_V(8); PG8_WAIT_L(0); PG8_BAR; PG8_MMA(0, 0, At, B0); PG8_MMA(0, 1, At, B1); PG8_BAR; PG8_SCHED;
;             PG8_LDA(At, 0, 1); PG8_STAGE(PG8_SB(0, 0), b2, voffB); PG8_STAGE(PG8_SB(0, 1), b2 + hstepB, voffB); PG8_STAGE(PG8_SA(0, 0), a2, voffA);
;             PG8_WAIT_V(8); PG8_WAIT_L(0); PG8_BAR; PG8_MMA(1, 0, At, B0); PG8_MMA(1, 1, At, B1); PG8_BAR; PG8_SCHED;
;             PG8_LDB(B0, 1, 0); PG8_LDB(B1, 1, 1); PG8_SCHED; PG8_LDA(At, 1, 0); PG8_STAGE(PG8_SA(0, 1), a2 + hstepA, voffA);
;             PG8_WAIT_V(8); PG8_WAIT_L(0); PG8_BAR; PG8_MMA(0, 0, At, B0); PG8_MMA(0, 1, At, B1); PG8_BAR; PG8_SCHED;
;             PG8_LDA(At, 1, 1); PG8_STAGE(PG8_SB(1, 0), b3, voffB); PG8_STAGE(PG8_SB(1, 1), b3 + hstepB, voffB); PG8_STAGE(PG8_SA(1, 0), a3, voffA);
;             PG8_WAIT_V(8); PG8_WAIT_L(0); PG8_BAR; PG8_MMA(1, 0, At, B0); PG8_MMA(1, 1, At, B1); PG8_BAR; PG8_SCHED;
.LBB0_738:
	s_add_i32 s34, s20, 2
	s_add_u32 s35, s18, 0x80
	s_addc_u32 s21, s19, 0
	s_add_i32 s41, 0, 0x10000
	s_cmp_eq_u32 s64, s20
	s_cselect_b32 s21, s15, s21
	s_cselect_b32 s20, s14, s35
	s_cselect_b32 s45, s17, s29
	s_cselect_b32 s44, s16, s23
	s_add_i32 s35, 0, 0x14000
	s_waitcnt lgkmcnt(0)
	s_add_i32 m0, s30, 0xc000
	s_nop 0
	global_load_lds_dwordx4 v150, s[18:19]
	s_add_i32 m0, s30, 0xe000
	s_nop 0
	global_load_lds_dwordx4 v152, s[18:19]
	v_add_u32_e32 v136, s41, v182
	ds_read_b128 v[128:131], v136
	ds_read_b128 v[132:135], v136 offset:1024
	ds_read_b128 v[156:159], v136 offset:2048
	ds_read_b128 v[160:163], v136 offset:3072
	v_add_u32_e32 v136, s35, v182
	ds_read_b128 v[164:167], v136
	ds_read_b128 v[168:171], v136 offset:1024
	ds_read_b128 v[172:175], v136 offset:2048
	ds_read_b128 v[176:179], v136 offset:3072
	ds_read_b128 v[190:193], v188
	ds_read_b128 v[194:197], v188 offset:1024
	ds_read_b128 v[198:201], v188 offset:2048
	ds_read_b128 v[202:205], v188 offset:3072
	ds_read_b128 v[206:209], v188 offset:4096
	ds_read_b128 v[224:227], v188 offset:5120
	ds_read_b128 v[228:231], v188 offset:6144
	ds_read_b128 v[232:235], v188 offset:7168
	s_waitcnt vmcnt(8)
	s_waitcnt lgkmcnt(0)
	s_barrier
	s_setprio 1
	s_waitcnt lgkmcnt(0)
	v_mfma_f32_16x16x32_bf16 v[124:127], v[128:131], v[190:193], v[124:127]
	v_mfma_f32_16x16x32_bf16 v[120:123], v[156:159], v[190:193], v[120:123]
	v_mfma_f32_16x16x32_bf16 v[108:111], v[128:131], v[198:201], v[108:111]
	v_mfma_f32_16x16x32_bf16 v[104:107], v[156:159], v[198:201], v[104:107]
	v_mfma_f32_16x16x32_bf16 v[92:95], v[128:131], v[206:209], v[92:95]
	v_mfma_f32_16x16x32_bf16 v[88:91], v[156:159], v[206:209], v[88:91]
	v_mfma_f32_16x16x32_bf16 v[76:79], v[128:131], v[228:231], v[76:79]
	v_mfma_f32_16x16x32_bf16 v[72:75], v[156:159], v[228:231], v[72:75]
	v_mfma_f32_16x16x32_bf16 v[124:127], v[132:135], v[194:197], v[124:127]
	v_mfma_f32_16x16x32_bf16 v[120:123], v[160:163], v[194:197], v[120:123]
	v_mfma_f32_16x16x32_bf16 v[108:111], v[132:135], v[202:205], v[108:111]
	v_mfma_f32_16x16x32_bf16 v[104:107], v[160:163], v[202:205], v[104:107]
	v_mfma_f32_16x16x32_bf16 v[92:95], v[132:135], v[224:227], v[92:95]
	v_mfma_f32_16x16x32_bf16 v[88:91], v[160:163], v[224:227], v[88:91]
	v_mfma_f32_16x16x32_bf16 v[76:79], v[132:135], v[232:235], v[76:79]
	v_mfma_f32_16x16x32_bf16 v[72:75], v[160:163], v[232:235], v[72:75]
	s_setprio 0
	s_setprio 1
	v_mfma_f32_16x16x32_bf16 v[116:119], v[164:167], v[190:193], v[116:119]
	v_mfma_f32_16x16x32_bf16 v[112:115], v[172:175], v[190:193], v[112:115]
	v_mfma_f32_16x16x32_bf16 v[100:103], v[164:167], v[198:201], v[100:103]
	v_mfma_f32_16x16x32_bf16 v[96:99], v[172:175], v[198:201], v[96:99]
	v_mfma_f32_16x16x32_bf16 v[84:87], v[164:167], v[206:209], v[84:87]
	v_mfma_f32_16x16x32_bf16 v[80:83], v[172:175], v[206:209], v[80:83]
	v_mfma_f32_16x16x32_bf16 v[68:71], v[164:167], v[228:231], v[68:71]
	v_mfma_f32_16x16x32_bf16 v[64:67], v[172:175], v[228:231], v[64:67]
	v_mfma_f32_16x16x32_bf16 v[116:119], v[168:171], v[194:197], v[116:119]
	v_mfma_f32_16x16x32_bf16 v[112:115], v[176:179], v[194:197], v[112:115]
	v_mfma_f32_16x16x32_bf16 v[100:103], v[168:171], v[202:205], v[100:103]
	v_mfma_f32_16x16x32_bf16 v[96:99], v[176:179], v[202:205], v[96:99]
	v_mfma_f32_16x16x32_bf16 v[84:87], v[168:171], v[224:227], v[84:87]
	v_mfma_f32_16x16x32_bf16 v[80:83], v[176:179], v[224:227], v[80:83]
	v_mfma_f32_16x16x32_bf16 v[68:71], v[168:171], v[232:235], v[68:71]
	v_mfma_f32_16x16x32_bf16 v[64:67], v[176:179], v[232:235], v[64:67]
	s_setprio 0
	s_barrier
	s_add_i32 s41, s41, s28
	s_mov_b32 m0, s41
	s_nop 0
	global_load_lds_dwordx4 v140, s[44:45]
	s_add_i32 m0, s41, 0x2000
	s_add_i32 s35, s35, s28
	global_load_lds_dwordx4 v144, s[44:45]
	s_add_u32 s44, s44, s26
	s_addc_u32 s45, s45, 0
	s_mov_b32 m0, s35
	s_nop 0
	global_load_lds_dwordx4 v140, s[44:45]
	s_add_i32 m0, s35, 0x2000
	s_nop 0
	global_load_lds_dwordx4 v144, s[44:45]
	s_mov_b32 m0, s30
	s_nop 0
	global_load_lds_dwordx4 v138, s[20:21]
	s_mov_b32 m0, s31
	s_nop 0
	global_load_lds_dwordx4 v142, s[20:21]
	ds_read_b128 v[190:193], v188 offset:16384
	ds_read_b128 v[194:197], v188 offset:17408
	ds_read_b128 v[198:201], v188 offset:18432
	ds_read_b128 v[202:205], v188 offset:19456
	ds_read_b128 v[206:209], v188 offset:20480
	ds_read_b128 v[224:227], v188 offset:21504
	ds_read_b128 v[228:231], v188 offset:22528
	ds_read_b128 v[232:235], v188 offset:23552
	s_waitcnt vmcnt(8)
	s_waitcnt lgkmcnt(0)
	s_barrier
	s_setprio 1
	s_waitcnt lgkmcnt(0)
	v_mfma_f32_16x16x32_bf16 v[60:63], v[128:131], v[190:193], v[60:63]
	v_mfma_f32_16x16x32_bf16 v[56:59], v[156:159], v[190:193], v[56:59]
	v_mfma_f32_16x16x32_bf16 v[44:47], v[128:131], v[198:201], v[44:47]
	v_mfma_f32_16x16x32_bf16 v[40:43], v[156:159], v[198:201], v[40:43]
	v_mfma_f32_16x16x32_bf16 v[28:31], v[128:131], v[206:209], v[28:31]
	v_mfma_f32_16x16x32_bf16 v[24:27], v[156:159], v[206:209], v[24:27]
	v_mfma_f32_16x16x32_bf16 v[12:15], v[128:131], v[228:231], v[12:15]
	v_mfma_f32_16x16x32_bf16 v[8:11], v[156:159], v[228:231], v[8:11]
	v_mfma_f32_16x16x32_bf16 v[60:63], v[132:135], v[194:197], v[60:63]
	v_mfma_f32_16x16x32_bf16 v[56:59], v[160:163], v[194:197], v[56:59]
	v_mfma_f32_16x16x32_bf16 v[44:47], v[132:135], v[202:205], v[44:47]
	v_mfma_f32_16x16x32_bf16 v[40:43], v[160:163], v[202:205], v[40:43]
	v_mfma_f32_16x16x32_bf16 v[28:31], v[132:135], v[224:227], v[28:31]
	v_mfma_f32_16x16x32_bf16 v[24:27], v[160:163], v[224:227], v[24:27]
	v_mfma_f32_16x16x32_bf16 v[12:15], v[132:135], v[232:235], v[12:15]
	v_mfma_f32_16x16x32_bf16 v[8:11], v[160:163], v[232:235], v[8:11]
	s_setprio 0
	s_setprio 1
	v_mfma_f32_16x16x32_bf16 v[52:55], v[164:167], v[190:193], v[52:55]
	v_mfma_f32_16x16x32_bf16 v[48:51], v[172:175], v[190:193], v[48:51]
	v_mfma_f32_16x16x32_bf16 v[36:39], v[164:167], v[198:201], v[36:39]
	v_mfma_f32_16x16x32_bf16 v[32:35], v[172:175], v[198:201], v[32:35]
	v_mfma_f32_16x16x32_bf16 v[20:23], v[164:167], v[206:209], v[20:23]
	v_mfma_f32_16x16x32_bf16 v[16:19], v[172:175], v[206:209], v[16:19]
	v_mfma_f32_16x16x32_bf16 v[4:7], v[164:167], v[228:231], v[4:7]
	v_mfma_f32_16x16x32_bf16 v[0:3], v[172:175], v[228:231], v[0:3]
	v_mfma_f32_16x16x32_bf16 v[52:55], v[168:171], v[194:197], v[52:55]
	v_mfma_f32_16x16x32_bf16 v[48:51], v[176:179], v[194:197], v[48:51]
	v_mfma_f32_16x16x32_bf16 v[36:39], v[168:171], v[202:205], v[36:39]
	v_mfma_f32_16x16x32_bf16 v[32:35], v[176:179], v[202:205], v[32:35]
	v_mfma_f32_16x16x32_bf16 v[20:23], v[168:171], v[224:227], v[20:23]
	v_mfma_f32_16x16x32_bf16 v[16:19], v[176:179], v[224:227], v[16:19]
	v_mfma_f32_16x16x32_bf16 v[4:7], v[168:171], v[232:235], v[4:7]
	v_mfma_f32_16x16x32_bf16 v[0:3], v[176:179], v[232:235], v[0:3]
	s_setprio 0
	s_barrier
; #define PG8_STAGE(bufoff, gbase, voff) do { _Pragma("unroll") for (int _i = 0; _i < 2; ++_i) \
;         __builtin_amdgcn_global_load_lds((const unsigned*)((const char*)(gbase) + (voff)[_i]), (LAS unsigned*)(lds + (bufoff) + ldsw + _i * 8192), 16, 0, 0); } while (0)
; #define PG8_LDA(dst, b, h) do { _Pragma("unroll") for (int m = 0; m < 4; ++m) _Pragma("unroll") for (int k = 0; k < 2; ++k) dst[m][k] = *(const LAS bf16x8*)(lds + PG8_SA(b, h) + aoff + m * 2048 + k * 1024); } while (0)
; #define PG8_LDB(dst, b, h) do { _Pragma("unroll") for (int n = 0; n < 2; ++n) _Pragma("unroll") for (int k = 0; k < 2; ++k) dst[n][k] = *(const LAS bf16x8*)(lds + PG8_SB(b, h) + boff + n * 2048 + k * 1024); } while (0)
; #define PG8_WAIT_V(n) asm volatile("s_waitcnt vmcnt(" #n ")" ::: "memory")
; #define PG8_BAR __builtin_amdgcn_s_barrier()
; template <class Epi>
; __device__ __forceinline__ void gemm_phase(LAS unsigned char* lds, const Gemm g, const StaticOrder& S, const Epi& E, const int tid) {
;     ...
;         for (int t = 0; t < nt; t += 2) {
;             const bool last = (t == nt - 2);
;             const char* a1 = cA + (size_t)(t + 1) * kstep;
;             const char* a2 = last ? nA : cA + (size_t)(t + 2) * kstep; const char* b2 = last ? nB : cB + (size_t)(t + 2) * kstep;
;             const char* a3 = a2 + kstep; const char* b3 = b2 + kstep;
;             PG8_LDB(B0, 0, 0); PG8_LDB(B1, 0, 1); PG8_SCHED; PG8_LDA(At, 0, 0); PG8_STAGE(PG8_SA(1, 1), a1 + hstepA, voffA);
;             PG8_WAIT_V(8); PG8_WAIT_L(0); PG8_BAR; PG8_MMA(0, 0, At, B0); PG8_MMA(0, 1, At, B1); PG8_BAR; PG8_SCHED;
;             PG8_LDA(At, 0, 1); PG8_STAGE(PG8_SB(0, 0), b2, voffB); PG8_STAGE(PG8_SB(0, 1), b2 + hstepB, voffB); PG8_STAGE(PG8_SA(0, 0), a2, voffA);
;             PG8_WAIT_V(8); PG8_WAIT_L(0); PG8_BAR; PG8_MMA(1, 0, At, B0); PG8_MMA(1, 1, At, B1); PG8_BAR; PG8_SCHED;
;             PG8_LDB(B0, 1, 0); PG8_LDB(B1, 1, 1); PG8_SCHED; PG8_LDA(At, 1, 0); PG8_STAGE(PG8_SA(0, 1), a2 + hstepA, voffA);
;             PG8_WAIT_V(8); PG8_WAIT_L(0); PG8_BAR; PG8_MMA(0, 0, At, B0); PG8_MMA(0, 1, At, B1); PG8_BAR; PG8_SCHED;
;             PG8_LDA(At, 1, 1); PG8_STAGE(PG8_SB(1, 0), b3, voffB); PG8_STAGE(PG8_SB(1, 1), b3 + hstepB, voffB); PG8_STAGE(PG8_SA(1, 0), a3, voffA);
;             PG8_WAIT_V(8); PG8_WAIT_L(0); PG8_BAR; PG8_MMA(1, 0, At, B0); PG8_MMA(1, 1, At, B1); PG8_BAR; PG8_SCHED;
	s_add_i32 s35, 0, 0x18000
	s_add_i32 s41, 0, 0x1c000
	s_add_u32 s20, s20, s80
	s_addc_u32 s21, s21, 0
	s_mov_b32 m0, s38
	s_nop 0
	global_load_lds_dwordx4 v138, s[20:21]
	s_mov_b32 m0, s39
	s_nop 0
	global_load_lds_dwordx4 v142, s[20:21]
	v_add_u32_e32 v155, s35, v182
	ds_read_b128 v[128:131], v155
	ds_read_b128 v[132:135], v155 offset:1024
	ds_read_b128 v[156:159], v155 offset:2048
	ds_read_b128 v[160:163], v155 offset:3072
	v_add_u32_e32 v155, s41, v182
	ds_read_b128 v[164:167], v155
	ds_read_b128 v[168:171], v155 offset:1024
	ds_read_b128 v[172:175], v155 offset:2048
	ds_read_b128 v[176:179], v155 offset:3072
	ds_read_b128 v[190:193], v188 offset:32768
	ds_read_b128 v[194:197], v188 offset:33792
	ds_read_b128 v[198:201], v188 offset:34816
	ds_read_b128 v[202:205], v188 offset:35840
	ds_read_b128 v[206:209], v188 offset:36864
	ds_read_b128 v[224:227], v188 offset:37888
	ds_read_b128 v[228:231], v188 offset:38912
	ds_read_b128 v[232:235], v188 offset:39936
	s_waitcnt vmcnt(8)
	s_waitcnt lgkmcnt(0)
	s_barrier
	s_setprio 1
	s_waitcnt lgkmcnt(0)
	v_mfma_f32_16x16x32_bf16 v[124:127], v[128:131], v[190:193], v[124:127]
	v_mfma_f32_16x16x32_bf16 v[120:123], v[156:159], v[190:193], v[120:123]
	v_mfma_f32_16x16x32_bf16 v[108:111], v[128:131], v[198:201], v[108:111]
	v_mfma_f32_16x16x32_bf16 v[104:107], v[156:159], v[198:201], v[104:107]
	v_mfma_f32_16x16x32_bf16 v[92:95], v[128:131], v[206:209], v[92:95]
	v_mfma_f32_16x16x32_bf16 v[88:91], v[156:159], v[206:209], v[88:91]
	v_mfma_f32_16x16x32_bf16 v[76:79], v[128:131], v[228:231], v[76:79]
	v_mfma_f32_16x16x32_bf16 v[72:75], v[156:159], v[228:231], v[72:75]
	v_mfma_f32_16x16x32_bf16 v[124:127], v[132:135], v[194:197], v[124:127]
	v_mfma_f32_16x16x32_bf16 v[120:123], v[160:163], v[194:197], v[120:123]
	v_mfma_f32_16x16x32_bf16 v[108:111], v[132:135], v[202:205], v[108:111]
	v_mfma_f32_16x16x32_bf16 v[104:107], v[160:163], v[202:205], v[104:107]
	v_mfma_f32_16x16x32_bf16 v[92:95], v[132:135], v[224:227], v[92:95]
	v_mfma_f32_16x16x32_bf16 v[88:91], v[160:163], v[224:227], v[88:91]
	v_mfma_f32_16x16x32_bf16 v[76:79], v[132:135], v[232:235], v[76:79]
	v_mfma_f32_16x16x32_bf16 v[72:75], v[160:163], v[232:235], v[72:75]
	s_setprio 0
	s_setprio 1
	v_mfma_f32_16x16x32_bf16 v[116:119], v[164:167], v[190:193], v[116:119]
	v_mfma_f32_16x16x32_bf16 v[112:115], v[172:175], v[190:193], v[112:115]
	v_mfma_f32_16x16x32_bf16 v[100:103], v[164:167], v[198:201], v[100:103]
	v_mfma_f32_16x16x32_bf16 v[96:99], v[172:175], v[198:201], v[96:99]
	v_mfma_f32_16x16x32_bf16 v[84:87], v[164:167], v[206:209], v[84:87]
	v_mfma_f32_16x16x32_bf16 v[80:83], v[172:175], v[206:209], v[80:83]
	v_mfma_f32_16x16x32_bf16 v[68:71], v[164:167], v[228:231], v[68:71]
	v_mfma_f32_16x16x32_bf16 v[64:67], v[172:175], v[228:231], v[64:67]
	v_mfma_f32_16x16x32_bf16 v[116:119], v[168:171], v[194:197], v[116:119]
	v_mfma_f32_16x16x32_bf16 v[112:115], v[176:179], v[194:197], v[112:115]
	v_mfma_f32_16x16x32_bf16 v[100:103], v[168:171], v[202:205], v[100:103]
	v_mfma_f32_16x16x32_bf16 v[96:99], v[176:179], v[202:205], v[96:99]
	v_mfma_f32_16x16x32_bf16 v[84:87], v[168:171], v[224:227], v[84:87]
	v_mfma_f32_16x16x32_bf16 v[80:83], v[176:179], v[224:227], v[80:83]
	v_mfma_f32_16x16x32_bf16 v[68:71], v[168:171], v[232:235], v[68:71]
	v_mfma_f32_16x16x32_bf16 v[64:67], v[176:179], v[232:235], v[64:67]
	s_setprio 0
	s_barrier
	s_add_i32 s100, s35, s28
	s_sub_i32 m0, s100, 0x80
	s_sub_u32 s44, s44, s26
	s_subb_u32 s45, s45, 0
	global_load_lds_dwordx4 v140, s[44:45] offset:128
	s_add_i32 m0, s100, 0x1f80
	s_add_i32 s100, s41, s28
	global_load_lds_dwordx4 v144, s[44:45] offset:128
	s_add_u32 s44, s44, s26
	s_addc_u32 s45, s45, 0
	s_sub_i32 m0, s100, 0x80
	s_nop 0
	global_load_lds_dwordx4 v140, s[44:45] offset:128
	s_add_i32 m0, s100, 0x1f80
	s_sub_u32 s20, s20, s80
	global_load_lds_dwordx4 v144, s[44:45] offset:128
	s_subb_u32 s21, s21, 0
	s_sub_i32 m0, s8, 0x80
	s_nop 0
	global_load_lds_dwordx4 v138, s[20:21] offset:128
	s_sub_i32 m0, s9, 0x80
	s_nop 0
	global_load_lds_dwordx4 v142, s[20:21] offset:128
	ds_read_b128 v[190:193], v188 offset:49152
	ds_read_b128 v[194:197], v188 offset:50176
	ds_read_b128 v[198:201], v188 offset:51200
	ds_read_b128 v[202:205], v188 offset:52224
	ds_read_b128 v[206:209], v188 offset:53248
	ds_read_b128 v[224:227], v188 offset:54272
	ds_read_b128 v[228:231], v188 offset:55296
	ds_read_b128 v[232:235], v188 offset:56320
	s_waitcnt vmcnt(8)
	s_waitcnt lgkmcnt(0)
	s_barrier
	s_setprio 1
	s_waitcnt lgkmcnt(0)
	v_mfma_f32_16x16x32_bf16 v[60:63], v[128:131], v[190:193], v[60:63]
	v_mfma_f32_16x16x32_bf16 v[56:59], v[156:159], v[190:193], v[56:59]
	v_mfma_f32_16x16x32_bf16 v[44:47], v[128:131], v[198:201], v[44:47]
	v_mfma_f32_16x16x32_bf16 v[40:43], v[156:159], v[198:201], v[40:43]
	v_mfma_f32_16x16x32_bf16 v[28:31], v[128:131], v[206:209], v[28:31]
	v_mfma_f32_16x16x32_bf16 v[24:27], v[156:159], v[206:209], v[24:27]
	v_mfma_f32_16x16x32_bf16 v[12:15], v[128:131], v[228:231], v[12:15]
	v_mfma_f32_16x16x32_bf16 v[8:11], v[156:159], v[228:231], v[8:11]
	v_mfma_f32_16x16x32_bf16 v[60:63], v[132:135], v[194:197], v[60:63]
	v_mfma_f32_16x16x32_bf16 v[56:59], v[160:163], v[194:197], v[56:59]
	v_mfma_f32_16x16x32_bf16 v[44:47], v[132:135], v[202:205], v[44:47]
	v_mfma_f32_16x16x32_bf16 v[40:43], v[160:163], v[202:205], v[40:43]
	v_mfma_f32_16x16x32_bf16 v[28:31], v[132:135], v[224:227], v[28:31]
	v_mfma_f32_16x16x32_bf16 v[24:27], v[160:163], v[224:227], v[24:27]
	v_mfma_f32_16x16x32_bf16 v[12:15], v[132:135], v[232:235], v[12:15]
	v_mfma_f32_16x16x32_bf16 v[8:11], v[160:163], v[232:235], v[8:11]
	s_setprio 0
	s_setprio 1
	v_mfma_f32_16x16x32_bf16 v[52:55], v[164:167], v[190:193], v[52:55]
	v_mfma_f32_16x16x32_bf16 v[48:51], v[172:175], v[190:193], v[48:51]
	v_mfma_f32_16x16x32_bf16 v[36:39], v[164:167], v[198:201], v[36:39]
	v_mfma_f32_16x16x32_bf16 v[32:35], v[172:175], v[198:201], v[32:35]
	v_mfma_f32_16x16x32_bf16 v[20:23], v[164:167], v[206:209], v[20:23]
	v_mfma_f32_16x16x32_bf16 v[16:19], v[172:175], v[206:209], v[16:19]
	v_mfma_f32_16x16x32_bf16 v[4:7], v[164:167], v[228:231], v[4:7]
	v_mfma_f32_16x16x32_bf16 v[0:3], v[172:175], v[228:231], v[0:3]
	v_mfma_f32_16x16x32_bf16 v[52:55], v[168:171], v[194:197], v[52:55]
	v_mfma_f32_16x16x32_bf16 v[48:51], v[176:179], v[194:197], v[48:51]
	v_mfma_f32_16x16x32_bf16 v[36:39], v[168:171], v[202:205], v[36:39]
	v_mfma_f32_16x16x32_bf16 v[32:35], v[176:179], v[202:205], v[32:35]
	v_mfma_f32_16x16x32_bf16 v[20:23], v[168:171], v[224:227], v[20:23]
	v_mfma_f32_16x16x32_bf16 v[16:19], v[176:179], v[224:227], v[16:19]
	v_mfma_f32_16x16x32_bf16 v[4:7], v[168:171], v[232:235], v[4:7]
	v_mfma_f32_16x16x32_bf16 v[0:3], v[176:179], v[232:235], v[0:3]
	s_setprio 0
	s_barrier
	s_add_u32 s18, s18, 0x100
	s_addc_u32 s19, s19, 0
	s_add_u32 s23, s23, 0x100
	s_addc_u32 s29, s29, 0
	s_cmp_ge_u32 s34, s12
	s_mov_b32 s20, s34
	s_cbranch_scc0 .LBB0_738
	s_and_b64 vcc, exec, s[6:7]
	s_cbranch_vccz .LBB0_741
	s_barrier

; __global__ void __launch_bounds__(512, 2) hybrid_fwd(Args args) {
	.amdhsa_kernel _Z10hybrid_fwd4Args
		.amdhsa_group_segment_fixed_size 0
		.amdhsa_private_segment_fixed_size 0
		.amdhsa_kernarg_size 544
		.amdhsa_user_sgpr_count 2
		.amdhsa_user_sgpr_dispatch_ptr 0
		.amdhsa_user_sgpr_queue_ptr 0
		.amdhsa_user_sgpr_kernarg_segment_ptr 1
		.amdhsa_user_sgpr_dispatch_id 0
		.amdhsa_user_sgpr_kernarg_preload_length 0
		.amdhsa_user_sgpr_kernarg_preload_offset 0
		.amdhsa_user_sgpr_private_segment_size 0
		.amdhsa_uses_dynamic_stack 0
		.amdhsa_enable_private_segment 0
		.amdhsa_system_sgpr_workgroup_id_x 1
		.amdhsa_system_sgpr_workgroup_id_y 0
		.amdhsa_system_sgpr_workgroup_id_z 0
		.amdhsa_system_sgpr_workgroup_info 0
		.amdhsa_system_vgpr_workitem_id 2
		.amdhsa_next_free_vgpr 256
		.amdhsa_next_free_sgpr 102
		.amdhsa_accum_offset 256
		.amdhsa_reserve_vcc 1
		.amdhsa_float_round_mode_32 0
		.amdhsa_float_round_mode_16_64 0
		.amdhsa_float_denorm_mode_32 3
		.amdhsa_float_denorm_mode_16_64 3
		.amdhsa_dx10_clamp 1
		.amdhsa_ieee_mode 1
		.amdhsa_fp16_overflow 0
		.amdhsa_tg_split 0
		.amdhsa_exception_fp_ieee_invalid_op 0
		.amdhsa_exception_fp_denorm_src 0
		.amdhsa_exception_fp_ieee_div_zero 0
		.amdhsa_exception_fp_ieee_overflow 0
		.amdhsa_exception_fp_ieee_underflow 0
		.amdhsa_exception_fp_ieee_inexact 0
		.amdhsa_exception_int_div_zero 0
	.end_amdhsa_kernel

; __global__ void __launch_bounds__(512, 2) hybrid_fwd(Args args) {
amdhsa.kernels:
  - .agpr_count:     0
    .args:
      - .offset:         0
        .size:           288
        .value_kind:     by_value
      - .offset:         288
        .size:           4
        .value_kind:     hidden_block_count_x
      - .offset:         292
        .size:           4
        .value_kind:     hidden_block_count_y
      - .offset:         296
        .size:           4
        .value_kind:     hidden_block_count_z
      - .offset:         300
        .size:           2
        .value_kind:     hidden_group_size_x
      - .offset:         302
        .size:           2
        .value_kind:     hidden_group_size_y
      - .offset:         304
        .size:           2
        .value_kind:     hidden_group_size_z
      - .offset:         306
        .size:           2
        .value_kind:     hidden_remainder_x
      - .offset:         308
        .size:           2
        .value_kind:     hidden_remainder_y
      - .offset:         310
        .size:           2
        .value_kind:     hidden_remainder_z
      - .offset:         328
        .size:           8
        .value_kind:     hidden_global_offset_x
      - .offset:         336
        .size:           8
        .value_kind:     hidden_global_offset_y
      - .offset:         344
        .size:           8
        .value_kind:     hidden_global_offset_z
      - .offset:         352
        .size:           2
        .value_kind:     hidden_grid_dims
      - .offset:         376
        .size:           8
        .value_kind:     hidden_multigrid_sync_arg
      - .offset:         408
        .size:           4
        .value_kind:     hidden_dynamic_lds_size
    .group_segment_fixed_size: 0
    .kernarg_segment_align: 8
    .kernarg_segment_size: 544
    .language:       OpenCL C
    .language_version:
      - 2
      - 0
    .max_flat_workgroup_size: 512
    .name:           _Z10hybrid_fwd4Args
    .private_segment_fixed_size: 0
    .sgpr_count:     108
    .sgpr_spill_count: 159
    .symbol:         _Z10hybrid_fwd4Args.kd
    .uniform_work_group_size: 1
    .uses_dynamic_stack: false
    .vgpr_count:     256
    .vgpr_spill_count: 0
    .wavefront_size: 64
